# P5 GEMM epilogue: both x load pairs of a row block issued together, counted waits
# baseline (speedup 1.0000x reference)
; #define PG8_STAGE(bufoff, gbase, voff) do { _Pragma("unroll") for (int _i = 0; _i < 2; ++_i) \
;     __builtin_amdgcn_global_load_lds((const unsigned*)((const char*)(gbase) + (voff)[_i]), (PG8_LAS unsigned*)(lds + (bufoff) + ldsw + _i * 8192), 16, 0, 0); } while (0)
; #define PG8_LDA(dst, b, h) do { _Pragma("unroll") for (int m = 0; m < 4; ++m) _Pragma("unroll") for (int k = 0; k < 2; ++k) dst[m][k] = *(const PG8_LAS bf16x8*)(lds + PG8_SA(b, h) + aoff + m * 2048 + k * 1024); } while (0)
; #define PG8_LDB(dst, b, h) do { _Pragma("unroll") for (int n = 0; n < 2; ++n) _Pragma("unroll") for (int k = 0; k < 2; ++k) dst[n][k] = *(const PG8_LAS bf16x8*)(lds + PG8_SB(b, h) + boff + n * 2048 + k * 1024); } while (0)
; #define PG8_MMA(ai, bj, At, Bt) do { __builtin_amdgcn_s_setprio(1); _Pragma("unroll") for (int m = 0; m < 4; ++m) _Pragma("unroll") for (int n = 0; n < 2; ++n) _Pragma("unroll") for (int k = 0; k < 2; ++k) \
;     acc[ai][bj][m][n] = __builtin_amdgcn_mfma_f32_16x16x32_bf16(Bt[n][k], At[m][k], acc[ai][bj][m][n], 0, 0, 0); __builtin_amdgcn_s_setprio(0); } while (0)
; #define PG8_WAIT_V(n) asm volatile("s_waitcnt vmcnt(" #n ")" ::: "memory")
; #define PG8_WAIT_L(n) asm volatile("s_waitcnt lgkmcnt(" #n ")" ::: "memory")
; #define PG8_BAR __builtin_amdgcn_s_barrier()
; #define PG8_SCHED __builtin_amdgcn_sched_barrier(0)
; template <class Epi>
; DI void gemm_phase(PG8_LAS unsigned char* lds, const Gemm g, const StaticOrder& S, const Epi& E) {
;     ...
;       PG8_LDB(B0, 0, 0); PG8_SCHED; PG8_LDA(At, 0, 0); PG8_STAGE(PG8_SA(1, 1), a1 + hstepA, voffA);
;       PG8_WAIT_L(8); PG8_BAR; PG8_WAIT_L(0); PG8_MMA(0, 0, At, B0); PG8_BAR; PG8_SCHED;
;       PG8_LDB(B1, 0, 1); PG8_STAGE(PG8_SB(0, 0), b2, voffB);
;       PG8_BAR; PG8_WAIT_L(0); PG8_MMA(0, 1, At, B1); PG8_BAR;
;       PG8_LDA(At, 0, 1); PG8_STAGE(PG8_SA(0, 0), a2, voffA);
;       PG8_BAR; PG8_WAIT_L(0); PG8_MMA(1, 0, At, B0); PG8_BAR; PG8_SCHED;
;       PG8_STAGE(PG8_SB(0, 1), b2 + hstepB, voffB);
;       PG8_WAIT_V(6); PG8_BAR; PG8_MMA(1, 1, At, B1); PG8_BAR;
;       PG8_LDB(B0, 1, 0); PG8_SCHED; PG8_LDA(At, 1, 0); PG8_STAGE(PG8_SA(0, 1), a2 + hstepA, voffA);
;       PG8_WAIT_L(8); PG8_BAR; PG8_WAIT_L(0); PG8_MMA(0, 0, At, B0); PG8_BAR; PG8_SCHED;
.LBB0_435:
	ds_read_b128 v[168:171], v151
	ds_read_b128 v[172:175], v152
	ds_read_b128 v[176:179], v153
	ds_read_b128 v[180:183], v154
	s_add_u32 s17, s76, 0xfff80080
	s_addc_u32 s22, s77, -1
	s_cmp_eq_u32 s15, 28
	s_cselect_b32 s81, s0, s22
	s_cselect_b32 s80, s1, s17
	s_cselect_b32 s79, s4, s7
	s_cselect_b32 s78, s5, s6
	s_mov_b32 m0, s96
	v_lshl_add_u64 v[146:147], s[76:77], 0, v[138:139]
	ds_read_b128 v[184:187], v149
	ds_read_b128 v[188:191], v149 offset:1024
	ds_read_b128 v[192:195], v149 offset:2048
	ds_read_b128 v[196:199], v149 offset:3072
	ds_read_b128 v[200:203], v149 offset:4096
	ds_read_b128 v[204:207], v149 offset:5120
	ds_read_b128 v[212:215], v149 offset:6144
	ds_read_b128 v[216:219], v149 offset:7168
	global_load_lds_dwordx4 v[146:147], off
	v_lshl_add_u64 v[146:147], s[76:77], 0, v[140:141]
	s_mov_b32 m0, s97
	s_nop 0
	global_load_lds_dwordx4 v[146:147], off
	s_waitcnt lgkmcnt(8)
	s_barrier
	s_waitcnt lgkmcnt(0)
	s_setprio 1
	s_waitcnt lgkmcnt(0)
	v_mfma_f32_16x16x32_bf16 v[124:127], v[168:171], v[184:187], v[124:127]
	v_mfma_f32_16x16x32_bf16 v[120:123], v[176:179], v[184:187], v[120:123]
	v_mfma_f32_16x16x32_bf16 v[108:111], v[168:171], v[192:195], v[108:111]
	v_mfma_f32_16x16x32_bf16 v[104:107], v[176:179], v[192:195], v[104:107]
	v_mfma_f32_16x16x32_bf16 v[92:95], v[168:171], v[200:203], v[92:95]
	v_mfma_f32_16x16x32_bf16 v[88:91], v[176:179], v[200:203], v[88:91]
	v_mfma_f32_16x16x32_bf16 v[76:79], v[168:171], v[212:215], v[76:79]
	v_mfma_f32_16x16x32_bf16 v[72:75], v[176:179], v[212:215], v[72:75]
	v_mfma_f32_16x16x32_bf16 v[124:127], v[172:175], v[188:191], v[124:127]
	v_mfma_f32_16x16x32_bf16 v[120:123], v[180:183], v[188:191], v[120:123]
	v_mfma_f32_16x16x32_bf16 v[108:111], v[172:175], v[196:199], v[108:111]
	v_mfma_f32_16x16x32_bf16 v[104:107], v[180:183], v[196:199], v[104:107]
	v_mfma_f32_16x16x32_bf16 v[92:95], v[172:175], v[204:207], v[92:95]
	v_mfma_f32_16x16x32_bf16 v[88:91], v[180:183], v[204:207], v[88:91]
	v_mfma_f32_16x16x32_bf16 v[76:79], v[172:175], v[216:219], v[76:79]
	v_mfma_f32_16x16x32_bf16 v[72:75], v[180:183], v[216:219], v[72:75]
	s_setprio 0
	s_barrier
	s_mov_b32 m0, s59
	v_lshl_add_u64 v[146:147], s[78:79], 0, v[130:131]
	ds_read_b128 v[220:223], v155
	ds_read_b128 v[224:227], v156
	ds_read_b128 v[228:231], v157
	ds_read_b128 v[232:235], v158
	global_load_lds_dwordx4 v[146:147], off
	v_lshl_add_u64 v[236:237], s[78:79], 0, v[134:135]
	s_mov_b32 m0, s75
	s_nop 0
	global_load_lds_dwordx4 v[236:237], off
	s_barrier
	s_waitcnt lgkmcnt(0)
	s_setprio 1
	s_waitcnt lgkmcnt(0)
	v_mfma_f32_16x16x32_bf16 v[116:119], v[220:223], v[184:187], v[116:119]
	v_mfma_f32_16x16x32_bf16 v[112:115], v[228:231], v[184:187], v[112:115]
	v_mfma_f32_16x16x32_bf16 v[100:103], v[220:223], v[192:195], v[100:103]
	v_mfma_f32_16x16x32_bf16 v[96:99], v[228:231], v[192:195], v[96:99]
	v_mfma_f32_16x16x32_bf16 v[84:87], v[220:223], v[200:203], v[84:87]
	v_mfma_f32_16x16x32_bf16 v[80:83], v[228:231], v[200:203], v[80:83]
	v_mfma_f32_16x16x32_bf16 v[68:71], v[220:223], v[212:215], v[68:71]
	v_mfma_f32_16x16x32_bf16 v[64:67], v[228:231], v[212:215], v[64:67]
	v_mfma_f32_16x16x32_bf16 v[116:119], v[224:227], v[188:191], v[116:119]
	v_mfma_f32_16x16x32_bf16 v[112:115], v[232:235], v[188:191], v[112:115]
	v_mfma_f32_16x16x32_bf16 v[100:103], v[224:227], v[196:199], v[100:103]
	v_mfma_f32_16x16x32_bf16 v[96:99], v[232:235], v[196:199], v[96:99]
	v_mfma_f32_16x16x32_bf16 v[84:87], v[224:227], v[204:207], v[84:87]
	v_mfma_f32_16x16x32_bf16 v[80:83], v[232:235], v[204:207], v[80:83]
	v_mfma_f32_16x16x32_bf16 v[68:71], v[224:227], v[216:219], v[68:71]
	v_mfma_f32_16x16x32_bf16 v[64:67], v[232:235], v[216:219], v[64:67]
	s_setprio 0
	s_mov_b32 m0, s35
	v_lshl_add_u64 v[238:239], s[80:81], 0, v[128:129]
	s_barrier
	ds_read_b128 v[184:187], v149 offset:16384
	ds_read_b128 v[188:191], v149 offset:17408
	ds_read_b128 v[192:195], v149 offset:18432
	ds_read_b128 v[196:199], v149 offset:19456
	ds_read_b128 v[200:203], v149 offset:20480
	ds_read_b128 v[204:207], v149 offset:21504
	ds_read_b128 v[212:215], v149 offset:22528
	ds_read_b128 v[216:219], v149 offset:23552
	global_load_lds_dwordx4 v[238:239], off
	v_lshl_add_u64 v[240:241], s[80:81], 0, v[132:133]
	s_mov_b32 m0, s82
	s_nop 0
	global_load_lds_dwordx4 v[240:241], off
	s_barrier
	s_waitcnt lgkmcnt(0)
	s_setprio 1
	s_waitcnt lgkmcnt(0)
	v_mfma_f32_16x16x32_bf16 v[60:63], v[168:171], v[184:187], v[60:63]
	v_mfma_f32_16x16x32_bf16 v[56:59], v[176:179], v[184:187], v[56:59]
	v_mfma_f32_16x16x32_bf16 v[44:47], v[168:171], v[192:195], v[44:47]
	v_mfma_f32_16x16x32_bf16 v[40:43], v[176:179], v[192:195], v[40:43]
	v_mfma_f32_16x16x32_bf16 v[28:31], v[168:171], v[200:203], v[28:31]
	v_mfma_f32_16x16x32_bf16 v[24:27], v[176:179], v[200:203], v[24:27]
	v_mfma_f32_16x16x32_bf16 v[12:15], v[168:171], v[212:215], v[12:15]
	v_mfma_f32_16x16x32_bf16 v[8:11], v[176:179], v[212:215], v[8:11]
	v_mfma_f32_16x16x32_bf16 v[60:63], v[172:175], v[188:191], v[60:63]
	v_mfma_f32_16x16x32_bf16 v[56:59], v[180:183], v[188:191], v[56:59]
	v_mfma_f32_16x16x32_bf16 v[44:47], v[172:175], v[196:199], v[44:47]
	v_mfma_f32_16x16x32_bf16 v[40:43], v[180:183], v[196:199], v[40:43]
	v_mfma_f32_16x16x32_bf16 v[28:31], v[172:175], v[204:207], v[28:31]
	v_mfma_f32_16x16x32_bf16 v[24:27], v[180:183], v[204:207], v[24:27]
	v_mfma_f32_16x16x32_bf16 v[12:15], v[172:175], v[216:219], v[12:15]
	v_mfma_f32_16x16x32_bf16 v[8:11], v[180:183], v[216:219], v[8:11]
	s_setprio 0
	s_barrier
; #define PG8_STAGE(bufoff, gbase, voff) do { _Pragma("unroll") for (int _i = 0; _i < 2; ++_i) \
;     __builtin_amdgcn_global_load_lds((const unsigned*)((const char*)(gbase) + (voff)[_i]), (PG8_LAS unsigned*)(lds + (bufoff) + ldsw + _i * 8192), 16, 0, 0); } while (0)
; #define PG8_LDA(dst, b, h) do { _Pragma("unroll") for (int m = 0; m < 4; ++m) _Pragma("unroll") for (int k = 0; k < 2; ++k) dst[m][k] = *(const PG8_LAS bf16x8*)(lds + PG8_SA(b, h) + aoff + m * 2048 + k * 1024); } while (0)
; #define PG8_LDB(dst, b, h) do { _Pragma("unroll") for (int n = 0; n < 2; ++n) _Pragma("unroll") for (int k = 0; k < 2; ++k) dst[n][k] = *(const PG8_LAS bf16x8*)(lds + PG8_SB(b, h) + boff + n * 2048 + k * 1024); } while (0)
; #define PG8_MMA(ai, bj, At, Bt) do { __builtin_amdgcn_s_setprio(1); _Pragma("unroll") for (int m = 0; m < 4; ++m) _Pragma("unroll") for (int n = 0; n < 2; ++n) _Pragma("unroll") for (int k = 0; k < 2; ++k) \
;     acc[ai][bj][m][n] = __builtin_amdgcn_mfma_f32_16x16x32_bf16(Bt[n][k], At[m][k], acc[ai][bj][m][n], 0, 0, 0); __builtin_amdgcn_s_setprio(0); } while (0)
; #define PG8_WAIT_V(n) asm volatile("s_waitcnt vmcnt(" #n ")" ::: "memory")
; #define PG8_WAIT_L(n) asm volatile("s_waitcnt lgkmcnt(" #n ")" ::: "memory")
; #define PG8_BAR __builtin_amdgcn_s_barrier()
; template <class Epi>
; DI void gemm_phase(PG8_LAS unsigned char* lds, const Gemm g, const StaticOrder& S, const Epi& E) {
;     ...
;       PG8_LDB(B1, 0, 1); PG8_STAGE(PG8_SB(0, 0), b2, voffB);
;       PG8_BAR; PG8_WAIT_L(0); PG8_MMA(0, 1, At, B1); PG8_BAR;
;       PG8_LDA(At, 0, 1); PG8_STAGE(PG8_SA(0, 0), a2, voffA);
;       PG8_BAR; PG8_WAIT_L(0); PG8_MMA(1, 0, At, B0); PG8_BAR; PG8_SCHED;
;       PG8_STAGE(PG8_SB(0, 1), b2 + hstepB, voffB);
;       PG8_WAIT_V(6); PG8_BAR; PG8_MMA(1, 1, At, B1); PG8_BAR;
;       PG8_LDB(B0, 1, 0); PG8_SCHED; PG8_LDA(At, 1, 0); PG8_STAGE(PG8_SA(0, 1), a2 + hstepA, voffA);
;       PG8_WAIT_L(8); PG8_BAR; PG8_WAIT_L(0); PG8_MMA(0, 0, At, B0); PG8_BAR; PG8_SCHED;
;       PG8_LDB(B1, 1, 1); PG8_STAGE(PG8_SB(1, 0), b3, voffB);
;       PG8_BAR; PG8_WAIT_L(0); PG8_MMA(0, 1, At, B1); PG8_BAR;
;       PG8_LDA(At, 1, 1); PG8_STAGE(PG8_SA(1, 0), a3, voffA);
;       PG8_BAR; PG8_WAIT_L(0); PG8_MMA(1, 0, At, B0); PG8_BAR; PG8_SCHED;
;       PG8_STAGE(PG8_SB(1, 1), b3 + hstepB, voffB);
;       PG8_WAIT_V(6); PG8_BAR; PG8_MMA(1, 1, At, B1); PG8_BAR;
	s_add_u32 s22, s78, 0x80000
	s_addc_u32 s23, s79, 0
	s_mov_b32 m0, s83
	v_lshl_add_u64 v[168:169], s[22:23], 0, v[130:131]
	global_load_lds_dwordx4 v[168:169], off
	v_lshl_add_u64 v[168:169], s[22:23], 0, v[134:135]
	s_mov_b32 m0, s84
	s_nop 0
	global_load_lds_dwordx4 v[168:169], off
	s_waitcnt vmcnt(6)
	s_barrier
	s_setprio 1
	v_mfma_f32_16x16x32_bf16 v[52:55], v[220:223], v[184:187], v[52:55]
	v_mfma_f32_16x16x32_bf16 v[48:51], v[228:231], v[184:187], v[48:51]
	v_mfma_f32_16x16x32_bf16 v[36:39], v[220:223], v[192:195], v[36:39]
	v_mfma_f32_16x16x32_bf16 v[32:35], v[228:231], v[192:195], v[32:35]
	v_mfma_f32_16x16x32_bf16 v[20:23], v[220:223], v[200:203], v[20:23]
	v_mfma_f32_16x16x32_bf16 v[16:19], v[228:231], v[200:203], v[16:19]
	v_mfma_f32_16x16x32_bf16 v[4:7], v[220:223], v[212:215], v[4:7]
	v_mfma_f32_16x16x32_bf16 v[0:3], v[228:231], v[212:215], v[0:3]
	v_mfma_f32_16x16x32_bf16 v[52:55], v[224:227], v[188:191], v[52:55]
	v_mfma_f32_16x16x32_bf16 v[48:51], v[232:235], v[188:191], v[48:51]
	v_mfma_f32_16x16x32_bf16 v[36:39], v[224:227], v[196:199], v[36:39]
	v_mfma_f32_16x16x32_bf16 v[32:35], v[232:235], v[196:199], v[32:35]
	v_mfma_f32_16x16x32_bf16 v[20:23], v[224:227], v[204:207], v[20:23]
	v_mfma_f32_16x16x32_bf16 v[16:19], v[232:235], v[204:207], v[16:19]
	v_mfma_f32_16x16x32_bf16 v[4:7], v[224:227], v[216:219], v[4:7]
	v_mfma_f32_16x16x32_bf16 v[0:3], v[232:235], v[216:219], v[0:3]
	s_setprio 0
	s_barrier
	ds_read_b128 v[168:171], v159
	ds_read_b128 v[172:175], v160
	ds_read_b128 v[176:179], v161
	ds_read_b128 v[180:183], v162
	s_add_u32 s22, s80, 0x80000
	s_addc_u32 s23, s81, 0
	s_mov_b32 m0, s85
	v_lshl_add_u64 v[220:221], s[22:23], 0, v[128:129]
	ds_read_b128 v[184:187], v149 offset:32768
	ds_read_b128 v[188:191], v149 offset:33792
	ds_read_b128 v[192:195], v149 offset:34816
	ds_read_b128 v[196:199], v149 offset:35840
	ds_read_b128 v[200:203], v149 offset:36864
	ds_read_b128 v[204:207], v149 offset:37888
	ds_read_b128 v[212:215], v149 offset:38912
	ds_read_b128 v[216:219], v149 offset:39936
	global_load_lds_dwordx4 v[220:221], off
	v_lshl_add_u64 v[220:221], s[22:23], 0, v[132:133]
	s_mov_b32 m0, s86
	s_nop 0
	global_load_lds_dwordx4 v[220:221], off
	s_waitcnt lgkmcnt(8)
	s_barrier
	s_waitcnt lgkmcnt(0)
	s_setprio 1
	s_waitcnt lgkmcnt(0)
	v_mfma_f32_16x16x32_bf16 v[124:127], v[168:171], v[184:187], v[124:127]
	v_mfma_f32_16x16x32_bf16 v[120:123], v[176:179], v[184:187], v[120:123]
	v_mfma_f32_16x16x32_bf16 v[108:111], v[168:171], v[192:195], v[108:111]
	v_mfma_f32_16x16x32_bf16 v[104:107], v[176:179], v[192:195], v[104:107]
	v_mfma_f32_16x16x32_bf16 v[92:95], v[168:171], v[200:203], v[92:95]
	v_mfma_f32_16x16x32_bf16 v[88:91], v[176:179], v[200:203], v[88:91]
	v_mfma_f32_16x16x32_bf16 v[76:79], v[168:171], v[212:215], v[76:79]
	v_mfma_f32_16x16x32_bf16 v[72:75], v[176:179], v[212:215], v[72:75]
	v_mfma_f32_16x16x32_bf16 v[124:127], v[172:175], v[188:191], v[124:127]
	v_mfma_f32_16x16x32_bf16 v[120:123], v[180:183], v[188:191], v[120:123]
	v_mfma_f32_16x16x32_bf16 v[108:111], v[172:175], v[196:199], v[108:111]
	v_mfma_f32_16x16x32_bf16 v[104:107], v[180:183], v[196:199], v[104:107]
	v_mfma_f32_16x16x32_bf16 v[92:95], v[172:175], v[204:207], v[92:95]
	v_mfma_f32_16x16x32_bf16 v[88:91], v[180:183], v[204:207], v[88:91]
	v_mfma_f32_16x16x32_bf16 v[76:79], v[172:175], v[216:219], v[76:79]
	v_mfma_f32_16x16x32_bf16 v[72:75], v[180:183], v[216:219], v[72:75]
	s_setprio 0
	s_barrier
	s_mov_b32 m0, s87
	v_lshl_add_u64 v[146:147], v[146:147], 0, s[12:13]
	ds_read_b128 v[220:223], v163
	ds_read_b128 v[224:227], v164
	ds_read_b128 v[228:231], v165
	ds_read_b128 v[232:235], v166
	global_load_lds_dwordx4 v[146:147], off
	v_lshl_add_u64 v[146:147], v[236:237], 0, s[12:13]
	s_mov_b32 m0, s88
	s_nop 0
	global_load_lds_dwordx4 v[146:147], off
	s_barrier
	s_waitcnt lgkmcnt(0)
	s_setprio 1
	s_waitcnt lgkmcnt(0)
	v_mfma_f32_16x16x32_bf16 v[116:119], v[220:223], v[184:187], v[116:119]
	v_mfma_f32_16x16x32_bf16 v[112:115], v[228:231], v[184:187], v[112:115]
	v_mfma_f32_16x16x32_bf16 v[100:103], v[220:223], v[192:195], v[100:103]
	v_mfma_f32_16x16x32_bf16 v[96:99], v[228:231], v[192:195], v[96:99]
	v_mfma_f32_16x16x32_bf16 v[84:87], v[220:223], v[200:203], v[84:87]
	v_mfma_f32_16x16x32_bf16 v[80:83], v[228:231], v[200:203], v[80:83]
	v_mfma_f32_16x16x32_bf16 v[68:71], v[220:223], v[212:215], v[68:71]
	v_mfma_f32_16x16x32_bf16 v[64:67], v[228:231], v[212:215], v[64:67]
	v_mfma_f32_16x16x32_bf16 v[116:119], v[224:227], v[188:191], v[116:119]
	v_mfma_f32_16x16x32_bf16 v[112:115], v[232:235], v[188:191], v[112:115]
	v_mfma_f32_16x16x32_bf16 v[100:103], v[224:227], v[196:199], v[100:103]
	v_mfma_f32_16x16x32_bf16 v[96:99], v[232:235], v[196:199], v[96:99]
	v_mfma_f32_16x16x32_bf16 v[84:87], v[224:227], v[204:207], v[84:87]
	v_mfma_f32_16x16x32_bf16 v[80:83], v[232:235], v[204:207], v[80:83]
	v_mfma_f32_16x16x32_bf16 v[68:71], v[224:227], v[216:219], v[68:71]
	v_mfma_f32_16x16x32_bf16 v[64:67], v[232:235], v[216:219], v[64:67]
	s_setprio 0
	s_mov_b32 m0, s89
	v_lshl_add_u64 v[146:147], v[238:239], 0, s[12:13]
	s_barrier
	ds_read_b128 v[184:187], v149 offset:49152
	ds_read_b128 v[188:191], v149 offset:50176
	ds_read_b128 v[192:195], v149 offset:51200
	ds_read_b128 v[196:199], v149 offset:52224
	ds_read_b128 v[200:203], v149 offset:53248
	ds_read_b128 v[204:207], v149 offset:54272
	ds_read_b128 v[212:215], v149 offset:55296
	ds_read_b128 v[216:219], v149 offset:56320
	global_load_lds_dwordx4 v[146:147], off
	v_lshl_add_u64 v[146:147], v[240:241], 0, s[12:13]
	s_mov_b32 m0, s90
	s_nop 0
	global_load_lds_dwordx4 v[146:147], off
	s_barrier
; #define PG8_MMA(ai, bj, At, Bt) do { __builtin_amdgcn_s_setprio(1); _Pragma("unroll") for (int m = 0; m < 4; ++m) _Pragma("unroll") for (int n = 0; n < 2; ++n) _Pragma("unroll") for (int k = 0; k < 2; ++k) \
;     acc[ai][bj][m][n] = __builtin_amdgcn_mfma_f32_16x16x32_bf16(Bt[n][k], At[m][k], acc[ai][bj][m][n], 0, 0, 0); __builtin_amdgcn_s_setprio(0); } while (0)
; #define PG8_WAIT_V(n) asm volatile("s_waitcnt vmcnt(" #n ")" ::: "memory")
; #define PG8_BAR __builtin_amdgcn_s_barrier()
; DI u32x4 pack8(const f32x4& a, const f32x4& b) { u32x4 w; w[0] = pk2(a[0], a[1]); w[1] = pk2(a[2], a[3]); w[2] = pk2(b[0], b[1]); w[3] = pk2(b[2], b[3]); return w; }
; template <class Epi>
; DI void gemm_phase(PG8_LAS unsigned char* lds, const Gemm g, const StaticOrder& S, const Epi& E) {
;     ...
;       PG8_WAIT_V(6); PG8_BAR; PG8_MMA(1, 1, At, B1); PG8_BAR;
;   DI void operator()(const f32x4 (&acc)[2][2][4][2], const Unit& u, int wr, int wc, int fr, int fq) const {
;     ...
;     for (int ai = 0; ai < 2; ++ai)
; #pragma unroll
;       for (int m = 0; m < 4; ++m) {
;         const int r = row0 + ai * HALF + m * 16;
;         float ss = 0.f;
; #pragma unroll
;         for (int bj = 0; bj < 2; ++bj) {
;           const u32 o = (u32)r * 2048u + (u32)(col0 + bj * HALF);
;           const f32x4 x0 = __builtin_nontemporal_load((const f32x4*)(x + o)), x1 = __builtin_nontemporal_load((const f32x4*)(x + o + 4));
;           const f32x4 v0 = x0 + acc[ai][bj][m][0], v1 = x1 + acc[ai][bj][m][1];
;           *(f32x4*)(out + o) = v0; *(f32x4*)(out + o + 4) = v1;
;           *(u32x4*)(x1b + o) = pack8(v0, v1);
;           ss += sq8(v0, v1);
;         }
;         ss += __shfl_xor(ss, 16); ss += __shfl_xor(ss, 32);
;         if (fq == 0) atomicAdd(ssq + r, ss);
;       }
	s_waitcnt lgkmcnt(0)
	s_setprio 1
	s_waitcnt lgkmcnt(0)
	v_mfma_f32_16x16x32_bf16 v[60:63], v[168:171], v[184:187], v[60:63]
	v_mfma_f32_16x16x32_bf16 v[56:59], v[176:179], v[184:187], v[56:59]
	v_mfma_f32_16x16x32_bf16 v[44:47], v[168:171], v[192:195], v[44:47]
	v_mfma_f32_16x16x32_bf16 v[40:43], v[176:179], v[192:195], v[40:43]
	v_mfma_f32_16x16x32_bf16 v[28:31], v[168:171], v[200:203], v[28:31]
	v_mfma_f32_16x16x32_bf16 v[24:27], v[176:179], v[200:203], v[24:27]
	v_mfma_f32_16x16x32_bf16 v[12:15], v[168:171], v[212:215], v[12:15]
	v_mfma_f32_16x16x32_bf16 v[8:11], v[176:179], v[212:215], v[8:11]
	v_mfma_f32_16x16x32_bf16 v[60:63], v[172:175], v[188:191], v[60:63]
	v_mfma_f32_16x16x32_bf16 v[56:59], v[180:183], v[188:191], v[56:59]
	v_mfma_f32_16x16x32_bf16 v[44:47], v[172:175], v[196:199], v[44:47]
	v_mfma_f32_16x16x32_bf16 v[40:43], v[180:183], v[196:199], v[40:43]
	v_mfma_f32_16x16x32_bf16 v[28:31], v[172:175], v[204:207], v[28:31]
	v_mfma_f32_16x16x32_bf16 v[24:27], v[180:183], v[204:207], v[24:27]
	v_mfma_f32_16x16x32_bf16 v[12:15], v[172:175], v[216:219], v[12:15]
	v_mfma_f32_16x16x32_bf16 v[8:11], v[180:183], v[216:219], v[8:11]
	s_setprio 0
	s_barrier
	s_add_u32 s22, s78, 0x80080
	s_addc_u32 s23, s79, 0
	s_mov_b32 m0, s91
	v_lshl_add_u64 v[146:147], s[22:23], 0, v[130:131]
	global_load_lds_dwordx4 v[146:147], off
	v_lshl_add_u64 v[146:147], s[22:23], 0, v[134:135]
	s_mov_b32 m0, s92
	s_nop 0
	global_load_lds_dwordx4 v[146:147], off
	s_waitcnt vmcnt(6)
	s_barrier
	s_setprio 1
	v_mfma_f32_16x16x32_bf16 v[52:55], v[220:223], v[184:187], v[52:55]
	v_mfma_f32_16x16x32_bf16 v[48:51], v[228:231], v[184:187], v[48:51]
	v_mfma_f32_16x16x32_bf16 v[36:39], v[220:223], v[192:195], v[36:39]
	v_mfma_f32_16x16x32_bf16 v[32:35], v[228:231], v[192:195], v[32:35]
	v_mfma_f32_16x16x32_bf16 v[20:23], v[220:223], v[200:203], v[20:23]
	v_mfma_f32_16x16x32_bf16 v[16:19], v[228:231], v[200:203], v[16:19]
	v_mfma_f32_16x16x32_bf16 v[4:7], v[220:223], v[212:215], v[4:7]
	v_mfma_f32_16x16x32_bf16 v[0:3], v[228:231], v[212:215], v[0:3]
	v_mfma_f32_16x16x32_bf16 v[52:55], v[224:227], v[188:191], v[52:55]
	v_mfma_f32_16x16x32_bf16 v[48:51], v[232:235], v[188:191], v[48:51]
	v_mfma_f32_16x16x32_bf16 v[36:39], v[224:227], v[196:199], v[36:39]
	v_mfma_f32_16x16x32_bf16 v[32:35], v[232:235], v[196:199], v[32:35]
	v_mfma_f32_16x16x32_bf16 v[20:23], v[224:227], v[204:207], v[20:23]
	v_mfma_f32_16x16x32_bf16 v[16:19], v[232:235], v[204:207], v[16:19]
	v_mfma_f32_16x16x32_bf16 v[4:7], v[224:227], v[216:219], v[4:7]
	v_mfma_f32_16x16x32_bf16 v[0:3], v[232:235], v[216:219], v[0:3]
	s_setprio 0
	s_add_i32 s15, s15, 2
	s_add_u32 s76, s76, 0x100
	s_addc_u32 s77, s77, 0
	s_add_u32 s6, s6, 0x100
	s_addc_u32 s7, s7, 0
	s_cmp_gt_u32 s15, 29
	s_barrier
	s_cbranch_scc0 .LBB0_435
	v_lshl_add_u32 v146, s72, 8, v148
	v_lshl_or_b32 v168, s74, 8, v150
	v_lshl_add_u32 v136, v146, 11, v168
	v_lshlrev_b64 v[178:179], 2, v[136:137]
	v_lshl_add_u64 v[180:181], s[36:37], 0, v[178:179]
	global_load_dwordx4 v[170:173], v[180:181], off nt
	global_load_dwordx4 v[174:177], v[180:181], off offset:16 nt
	global_load_dwordx4 v[236:239], v[180:181], off offset:512 nt
	global_load_dwordx4 v[240:243], v[180:181], off offset:528 nt
	v_lshl_add_u64 v[182:183], v[136:137], 1, s[42:43]
	v_lshl_add_u64 v[184:185], s[50:51], 0, v[178:179]
	v_or_b32_e32 v136, 0x80, v136
	s_waitcnt vmcnt(2)
	v_pk_add_f32 v[126:127], v[126:127], v[172:173]
	v_pk_add_f32 v[124:125], v[124:125], v[170:171]
	v_pk_add_f32 v[172:173], v[122:123], v[176:177]
	v_pk_add_f32 v[170:171], v[120:121], v[174:175]
	v_cvt_pk_bf16_f32 v120, v124, v125
	v_cvt_pk_bf16_f32 v121, v126, v127
	v_cvt_pk_bf16_f32 v122, v170, v171
	v_cvt_pk_bf16_f32 v123, v172, v173
	global_store_dwordx4 v[184:185], v[124:127], off
	global_store_dwordx4 v[184:185], v[170:173], off offset:16
	global_store_dwordx4 v[182:183], v[120:123], off
	s_waitcnt vmcnt(3)
	v_mov_b32_e32 v178, v240
	v_mov_b32_e32 v179, v241
	v_mov_b32_e32 v180, v242
	v_mov_b32_e32 v181, v243
	v_mov_b32_e32 v174, v236
	v_mov_b32_e32 v175, v237
	v_mov_b32_e32 v176, v238
	v_mov_b32_e32 v177, v239
	s_nop 0
	s_nop 0
	v_and_b32_e32 v121, 64, v167
	v_xor_b32_e32 v120, 16, v167
	v_add_u32_e32 v121, 64, v121
	v_xor_b32_e32 v122, 32, v167
	v_cmp_lt_i32_e32 vcc, v120, v121
	v_mul_f32_e32 v147, v125, v125
	v_fmac_f32_e32 v147, v124, v124
	v_cndmask_b32_e32 v120, v167, v120, vcc
	v_cmp_lt_i32_e32 vcc, v122, v121
	v_lshlrev_b32_e32 v121, 2, v120
	v_fmac_f32_e32 v147, v126, v126
	v_cndmask_b32_e32 v122, v167, v122, vcc
	v_lshlrev_b32_e32 v120, 2, v122
	v_fmac_f32_e32 v147, v127, v127
	v_fmac_f32_e32 v147, v170, v170
	v_fmac_f32_e32 v147, v171, v171
	v_fmac_f32_e32 v147, v172, v172
	v_fmac_f32_e32 v147, v173, v173
	s_nop 0
	v_pk_add_f32 v[116:117], v[116:117], v[174:175]
	v_pk_add_f32 v[122:123], v[112:113], v[178:179]
	v_mul_f32_e32 v112, v117, v117
	v_pk_add_f32 v[118:119], v[118:119], v[176:177]
	v_fmac_f32_e32 v112, v116, v116
	v_fmac_f32_e32 v112, v118, v118
	v_fmac_f32_e32 v112, v119, v119
	v_fmac_f32_e32 v112, v122, v122
	v_pk_add_f32 v[124:125], v[114:115], v[180:181]
	v_fmac_f32_e32 v112, v123, v123
	v_fmac_f32_e32 v112, v124, v124
	v_fmac_f32_e32 v112, v125, v125
	v_add_f32_e32 v112, v147, v112
	ds_bpermute_b32 v113, v121, v112
	global_store_dwordx4 v[184:185], v[116:119], off offset:512
	global_store_dwordx4 v[184:185], v[122:125], off offset:528
	v_cvt_pk_bf16_f32 v114, v116, v117
	v_cvt_pk_bf16_f32 v115, v118, v119
	v_cvt_pk_bf16_f32 v116, v122, v123
	s_waitcnt lgkmcnt(0)
	v_add_f32_e32 v112, v112, v113
	ds_bpermute_b32 v113, v120, v112
	v_cvt_pk_bf16_f32 v117, v124, v125
	v_lshl_add_u64 v[118:119], v[136:137], 1, s[42:43]
	global_store_dwordx4 v[118:119], v[114:117], off
	s_and_saveexec_b64 s[72:73], s[8:9]
	s_cbranch_execz .LBB0_438
	v_ashrrev_i32_e32 v147, 31, v146
	v_lshl_add_u64 v[114:115], v[146:147], 2, s[68:69]
	s_waitcnt lgkmcnt(0)
	v_add_f32_e32 v112, v112, v113
	global_atomic_add_f32 v[114:115], v112, off
; DI u32x4 pack8(const f32x4& a, const f32x4& b) { u32x4 w; w[0] = pk2(a[0], a[1]); w[1] = pk2(a[2], a[3]); w[2] = pk2(b[0], b[1]); w[3] = pk2(b[2], b[3]); return w; }
;   DI void operator()(const f32x4 (&acc)[2][2][4][2], const Unit& u, int wr, int wc, int fr, int fq) const {
;     ...
;     for (int ai = 0; ai < 2; ++ai)
; #pragma unroll
;       for (int m = 0; m < 4; ++m) {
;         const int r = row0 + ai * HALF + m * 16;
;         float ss = 0.f;
; #pragma unroll
;         for (int bj = 0; bj < 2; ++bj) {
;           const u32 o = (u32)r * 2048u + (u32)(col0 + bj * HALF);
;           const f32x4 x0 = __builtin_nontemporal_load((const f32x4*)(x + o)), x1 = __builtin_nontemporal_load((const f32x4*)(x + o + 4));
;           const f32x4 v0 = x0 + acc[ai][bj][m][0], v1 = x1 + acc[ai][bj][m][1];
;           *(f32x4*)(out + o) = v0; *(f32x4*)(out + o + 4) = v1;
;           *(u32x4*)(x1b + o) = pack8(v0, v1);
;           ss += sq8(v0, v1);
;         }
;         ss += __shfl_xor(ss, 16); ss += __shfl_xor(ss, 32);
;         if (fq == 0) atomicAdd(ssq + r, ss);
;       }
.LBB0_438:
	s_or_b64 exec, exec, s[72:73]
	v_or_b32_e32 v112, 16, v146
	v_lshl_add_u32 v136, v112, 11, v168
	v_lshlrev_b64 v[118:119], 2, v[136:137]
	v_lshl_add_u64 v[126:127], s[36:37], 0, v[118:119]
	global_load_dwordx4 v[114:117], v[126:127], off nt
	global_load_dwordx4 v[122:125], v[126:127], off offset:16 nt
	global_load_dwordx4 v[236:239], v[126:127], off offset:512 nt
	global_load_dwordx4 v[240:243], v[126:127], off offset:528 nt
	v_lshl_add_u64 v[170:171], v[136:137], 1, s[42:43]
	v_lshl_add_u64 v[118:119], s[50:51], 0, v[118:119]
	v_or_b32_e32 v136, 0x80, v136
	s_waitcnt vmcnt(3)
	v_pk_add_f32 v[110:111], v[110:111], v[116:117]
	v_pk_add_f32 v[108:109], v[108:109], v[114:115]
	s_waitcnt vmcnt(2)
	v_pk_add_f32 v[106:107], v[106:107], v[124:125]
	v_pk_add_f32 v[104:105], v[104:105], v[122:123]
	v_cvt_pk_bf16_f32 v114, v108, v109
	v_cvt_pk_bf16_f32 v115, v110, v111
	v_cvt_pk_bf16_f32 v116, v104, v105
	v_cvt_pk_bf16_f32 v117, v106, v107
	global_store_dwordx4 v[118:119], v[108:111], off
	global_store_dwordx4 v[118:119], v[104:107], off offset:16
	global_store_dwordx4 v[170:171], v[114:117], off
	s_waitcnt vmcnt(3)
	v_mov_b32_e32 v122, v240
	v_mov_b32_e32 v123, v241
	v_mov_b32_e32 v124, v242
	v_mov_b32_e32 v125, v243
	v_mov_b32_e32 v114, v236
	v_mov_b32_e32 v115, v237
	v_mov_b32_e32 v116, v238
	v_mov_b32_e32 v117, v239
	s_nop 0
	s_nop 0
	v_mul_f32_e32 v109, v109, v109
	v_fmac_f32_e32 v109, v108, v108
	v_fmac_f32_e32 v109, v110, v110
	v_fmac_f32_e32 v109, v111, v111
	v_fmac_f32_e32 v109, v104, v104
	v_fmac_f32_e32 v109, v105, v105
	v_fmac_f32_e32 v109, v106, v106
	v_fmac_f32_e32 v109, v107, v107
	s_nop 0
	v_pk_add_f32 v[100:101], v[100:101], v[114:115]
	s_nop 0
	v_pk_add_f32 v[104:105], v[96:97], v[122:123]
	v_mul_f32_e32 v96, v101, v101
	v_pk_add_f32 v[102:103], v[102:103], v[116:117]
	v_fmac_f32_e32 v96, v100, v100
	v_fmac_f32_e32 v96, v102, v102
	v_fmac_f32_e32 v96, v103, v103
	v_fmac_f32_e32 v96, v104, v104
	v_pk_add_f32 v[106:107], v[98:99], v[124:125]
	v_fmac_f32_e32 v96, v105, v105
	v_fmac_f32_e32 v96, v106, v106
	v_fmac_f32_e32 v96, v107, v107
	v_add_f32_e32 v96, v109, v96
	ds_bpermute_b32 v97, v121, v96
	global_store_dwordx4 v[118:119], v[100:103], off offset:512
	global_store_dwordx4 v[118:119], v[104:107], off offset:528
	v_cvt_pk_bf16_f32 v98, v100, v101
	v_cvt_pk_bf16_f32 v99, v102, v103
	v_cvt_pk_bf16_f32 v100, v104, v105
	s_waitcnt lgkmcnt(0)
	v_add_f32_e32 v96, v96, v97
	ds_bpermute_b32 v97, v120, v96
	v_cvt_pk_bf16_f32 v101, v106, v107
	v_lshl_add_u64 v[102:103], v[136:137], 1, s[42:43]
	global_store_dwordx4 v[102:103], v[98:101], off
	s_and_saveexec_b64 s[72:73], s[8:9]
	s_cbranch_execz .LBB0_440
	v_ashrrev_i32_e32 v113, 31, v112
	v_lshl_add_u64 v[98:99], v[112:113], 2, s[68:69]
	s_waitcnt lgkmcnt(0)
	v_add_f32_e32 v96, v96, v97
	global_atomic_add_f32 v[98:99], v96, off
.LBB0_440:
	s_or_b64 exec, exec, s[72:73]
	v_or_b32_e32 v96, 32, v146
	v_lshl_add_u32 v136, v96, 11, v168
	v_lshlrev_b64 v[106:107], 2, v[136:137]
	v_lshl_add_u64 v[108:109], s[36:37], 0, v[106:107]
	global_load_dwordx4 v[98:101], v[108:109], off nt
	global_load_dwordx4 v[102:105], v[108:109], off offset:16 nt
	global_load_dwordx4 v[236:239], v[108:109], off offset:512 nt
	global_load_dwordx4 v[240:243], v[108:109], off offset:528 nt
	v_lshl_add_u64 v[110:111], v[136:137], 1, s[42:43]
	v_lshl_add_u64 v[106:107], s[50:51], 0, v[106:107]
	v_or_b32_e32 v136, 0x80, v136
	s_waitcnt vmcnt(3)
	v_pk_add_f32 v[94:95], v[94:95], v[100:101]
	v_pk_add_f32 v[92:93], v[92:93], v[98:99]
	s_waitcnt vmcnt(2)
	v_pk_add_f32 v[90:91], v[90:91], v[104:105]
	v_pk_add_f32 v[88:89], v[88:89], v[102:103]
	v_cvt_pk_bf16_f32 v98, v92, v93
	v_cvt_pk_bf16_f32 v99, v94, v95
	v_cvt_pk_bf16_f32 v100, v88, v89
	v_cvt_pk_bf16_f32 v101, v90, v91
	global_store_dwordx4 v[106:107], v[92:95], off
	global_store_dwordx4 v[106:107], v[88:91], off offset:16
	global_store_dwordx4 v[110:111], v[98:101], off
	s_waitcnt vmcnt(3)
	v_mov_b32_e32 v102, v240
	v_mov_b32_e32 v103, v241
	v_mov_b32_e32 v104, v242
	v_mov_b32_e32 v105, v243
	v_mov_b32_e32 v98, v236
	v_mov_b32_e32 v99, v237
	v_mov_b32_e32 v100, v238
	v_mov_b32_e32 v101, v239
	s_nop 0
	s_nop 0
	v_mul_f32_e32 v93, v93, v93
	v_fmac_f32_e32 v93, v92, v92
	v_fmac_f32_e32 v93, v94, v94
	v_fmac_f32_e32 v93, v95, v95
	v_fmac_f32_e32 v93, v88, v88
	v_fmac_f32_e32 v93, v89, v89
	v_fmac_f32_e32 v93, v90, v90
	v_fmac_f32_e32 v93, v91, v91
	s_nop 0
	v_pk_add_f32 v[84:85], v[84:85], v[98:99]
	s_nop 0
	v_pk_add_f32 v[88:89], v[80:81], v[102:103]
	v_mul_f32_e32 v80, v85, v85
	v_pk_add_f32 v[86:87], v[86:87], v[100:101]
	v_fmac_f32_e32 v80, v84, v84
	v_fmac_f32_e32 v80, v86, v86
	v_fmac_f32_e32 v80, v87, v87
	v_fmac_f32_e32 v80, v88, v88
	v_pk_add_f32 v[90:91], v[82:83], v[104:105]
	v_fmac_f32_e32 v80, v89, v89
	v_fmac_f32_e32 v80, v90, v90
	v_fmac_f32_e32 v80, v91, v91
	v_add_f32_e32 v80, v93, v80
	ds_bpermute_b32 v81, v121, v80
	global_store_dwordx4 v[106:107], v[84:87], off offset:512
	global_store_dwordx4 v[106:107], v[88:91], off offset:528
	v_cvt_pk_bf16_f32 v82, v84, v85
	v_cvt_pk_bf16_f32 v83, v86, v87
	v_cvt_pk_bf16_f32 v84, v88, v89
	s_waitcnt lgkmcnt(0)
	v_add_f32_e32 v80, v80, v81
	ds_bpermute_b32 v81, v120, v80
	v_cvt_pk_bf16_f32 v85, v90, v91
	v_lshl_add_u64 v[86:87], v[136:137], 1, s[42:43]
	global_store_dwordx4 v[86:87], v[82:85], off
	s_and_saveexec_b64 s[72:73], s[8:9]
	s_cbranch_execz .LBB0_442
	v_ashrrev_i32_e32 v97, 31, v96
	v_lshl_add_u64 v[82:83], v[96:97], 2, s[68:69]
	s_waitcnt lgkmcnt(0)
	v_add_f32_e32 v80, v80, v81
	global_atomic_add_f32 v[82:83], v80, off
; DI u32x4 pack8(const f32x4& a, const f32x4& b) { u32x4 w; w[0] = pk2(a[0], a[1]); w[1] = pk2(a[2], a[3]); w[2] = pk2(b[0], b[1]); w[3] = pk2(b[2], b[3]); return w; }
;   DI void operator()(const f32x4 (&acc)[2][2][4][2], const Unit& u, int wr, int wc, int fr, int fq) const {
;     ...
;     for (int ai = 0; ai < 2; ++ai)
; #pragma unroll
;       for (int m = 0; m < 4; ++m) {
;         const int r = row0 + ai * HALF + m * 16;
;         float ss = 0.f;
; #pragma unroll
;         for (int bj = 0; bj < 2; ++bj) {
;           const u32 o = (u32)r * 2048u + (u32)(col0 + bj * HALF);
;           const f32x4 x0 = __builtin_nontemporal_load((const f32x4*)(x + o)), x1 = __builtin_nontemporal_load((const f32x4*)(x + o + 4));
;           const f32x4 v0 = x0 + acc[ai][bj][m][0], v1 = x1 + acc[ai][bj][m][1];
;           *(f32x4*)(out + o) = v0; *(f32x4*)(out + o + 4) = v1;
;           *(u32x4*)(x1b + o) = pack8(v0, v1);
;           ss += sq8(v0, v1);
;         }
;         ss += __shfl_xor(ss, 16); ss += __shfl_xor(ss, 32);
;         if (fq == 0) atomicAdd(ssq + r, ss);
;       }
.LBB0_442:
	s_or_b64 exec, exec, s[72:73]
	v_or_b32_e32 v80, 48, v146
	v_lshl_add_u32 v136, v80, 11, v168
	v_lshlrev_b64 v[90:91], 2, v[136:137]
	v_lshl_add_u64 v[92:93], s[36:37], 0, v[90:91]
	global_load_dwordx4 v[82:85], v[92:93], off nt
	global_load_dwordx4 v[86:89], v[92:93], off offset:16 nt
	global_load_dwordx4 v[236:239], v[92:93], off offset:512 nt
	global_load_dwordx4 v[240:243], v[92:93], off offset:528 nt
	v_lshl_add_u64 v[94:95], v[136:137], 1, s[42:43]
	v_lshl_add_u64 v[90:91], s[50:51], 0, v[90:91]
	v_or_b32_e32 v136, 0x80, v136
	s_waitcnt vmcnt(3)
	v_pk_add_f32 v[78:79], v[78:79], v[84:85]
	v_pk_add_f32 v[76:77], v[76:77], v[82:83]
	s_waitcnt vmcnt(2)
	v_pk_add_f32 v[74:75], v[74:75], v[88:89]
	v_pk_add_f32 v[72:73], v[72:73], v[86:87]
	v_cvt_pk_bf16_f32 v82, v76, v77
	v_cvt_pk_bf16_f32 v83, v78, v79
	v_cvt_pk_bf16_f32 v84, v72, v73
	v_cvt_pk_bf16_f32 v85, v74, v75
	global_store_dwordx4 v[90:91], v[76:79], off
	global_store_dwordx4 v[90:91], v[72:75], off offset:16
	global_store_dwordx4 v[94:95], v[82:85], off
	s_waitcnt vmcnt(3)
	v_mov_b32_e32 v86, v240
	v_mov_b32_e32 v87, v241
	v_mov_b32_e32 v88, v242
	v_mov_b32_e32 v89, v243
	v_mov_b32_e32 v82, v236
	v_mov_b32_e32 v83, v237
	v_mov_b32_e32 v84, v238
	v_mov_b32_e32 v85, v239
	s_nop 0
	s_nop 0
	v_mul_f32_e32 v77, v77, v77
	v_fmac_f32_e32 v77, v76, v76
	v_fmac_f32_e32 v77, v78, v78
	v_fmac_f32_e32 v77, v79, v79
	v_fmac_f32_e32 v77, v72, v72
	v_fmac_f32_e32 v77, v73, v73
	v_fmac_f32_e32 v77, v74, v74
	v_fmac_f32_e32 v77, v75, v75
	s_nop 0
	v_pk_add_f32 v[68:69], v[68:69], v[82:83]
	s_nop 0
	v_pk_add_f32 v[72:73], v[64:65], v[86:87]
	v_mul_f32_e32 v64, v69, v69
	v_pk_add_f32 v[70:71], v[70:71], v[84:85]
	v_fmac_f32_e32 v64, v68, v68
	v_fmac_f32_e32 v64, v70, v70
	v_fmac_f32_e32 v64, v71, v71
	v_fmac_f32_e32 v64, v72, v72
	v_pk_add_f32 v[74:75], v[66:67], v[88:89]
	v_fmac_f32_e32 v64, v73, v73
	v_fmac_f32_e32 v64, v74, v74
	v_fmac_f32_e32 v64, v75, v75
	v_add_f32_e32 v64, v77, v64
	ds_bpermute_b32 v65, v121, v64
	global_store_dwordx4 v[90:91], v[68:71], off offset:512
	global_store_dwordx4 v[90:91], v[72:75], off offset:528
	v_cvt_pk_bf16_f32 v66, v68, v69
	v_cvt_pk_bf16_f32 v67, v70, v71
	v_cvt_pk_bf16_f32 v68, v72, v73
	s_waitcnt lgkmcnt(0)
	v_add_f32_e32 v64, v64, v65
	ds_bpermute_b32 v65, v120, v64
	v_cvt_pk_bf16_f32 v69, v74, v75
	v_lshl_add_u64 v[70:71], v[136:137], 1, s[42:43]
	global_store_dwordx4 v[70:71], v[66:69], off
	s_and_saveexec_b64 s[72:73], s[8:9]
	s_cbranch_execz .LBB0_444
	v_ashrrev_i32_e32 v81, 31, v80
	v_lshl_add_u64 v[66:67], v[80:81], 2, s[68:69]
	s_waitcnt lgkmcnt(0)
	v_add_f32_e32 v64, v64, v65
	global_atomic_add_f32 v[66:67], v64, off
.LBB0_444:
	s_or_b64 exec, exec, s[72:73]
	v_add_u32_e32 v64, 0x80, v146
	v_lshl_add_u32 v136, v64, 11, v168
	v_lshlrev_b64 v[74:75], 2, v[136:137]
	v_lshl_add_u64 v[76:77], s[36:37], 0, v[74:75]
	global_load_dwordx4 v[66:69], v[76:77], off nt
	global_load_dwordx4 v[70:73], v[76:77], off offset:16 nt
	global_load_dwordx4 v[236:239], v[76:77], off offset:512 nt
	global_load_dwordx4 v[240:243], v[76:77], off offset:528 nt
	v_lshl_add_u64 v[78:79], v[136:137], 1, s[42:43]
	v_lshl_add_u64 v[74:75], s[50:51], 0, v[74:75]
	v_or_b32_e32 v136, 0x80, v136
	s_waitcnt vmcnt(3)
	v_pk_add_f32 v[62:63], v[62:63], v[68:69]
	v_pk_add_f32 v[60:61], v[60:61], v[66:67]
	s_waitcnt vmcnt(2)
	v_pk_add_f32 v[58:59], v[58:59], v[72:73]
	v_pk_add_f32 v[56:57], v[56:57], v[70:71]
	v_cvt_pk_bf16_f32 v66, v60, v61
	v_cvt_pk_bf16_f32 v67, v62, v63
	v_cvt_pk_bf16_f32 v68, v56, v57
	v_cvt_pk_bf16_f32 v69, v58, v59
	global_store_dwordx4 v[74:75], v[60:63], off
	global_store_dwordx4 v[74:75], v[56:59], off offset:16
	global_store_dwordx4 v[78:79], v[66:69], off
	s_waitcnt vmcnt(3)
	v_mov_b32_e32 v70, v240
	v_mov_b32_e32 v71, v241
	v_mov_b32_e32 v72, v242
	v_mov_b32_e32 v73, v243
	v_mov_b32_e32 v66, v236
	v_mov_b32_e32 v67, v237
	v_mov_b32_e32 v68, v238
	v_mov_b32_e32 v69, v239
	s_nop 0
	s_nop 0
	v_mul_f32_e32 v61, v61, v61
	v_fmac_f32_e32 v61, v60, v60
	v_fmac_f32_e32 v61, v62, v62
	v_fmac_f32_e32 v61, v63, v63
	v_fmac_f32_e32 v61, v56, v56
	v_fmac_f32_e32 v61, v57, v57
	v_fmac_f32_e32 v61, v58, v58
	v_fmac_f32_e32 v61, v59, v59
	s_nop 0
	v_pk_add_f32 v[52:53], v[52:53], v[66:67]
	s_nop 0
	v_pk_add_f32 v[56:57], v[48:49], v[70:71]
	v_mul_f32_e32 v48, v53, v53
	v_pk_add_f32 v[54:55], v[54:55], v[68:69]
	v_fmac_f32_e32 v48, v52, v52
	v_fmac_f32_e32 v48, v54, v54
	v_fmac_f32_e32 v48, v55, v55
	v_fmac_f32_e32 v48, v56, v56
	v_pk_add_f32 v[58:59], v[50:51], v[72:73]
	v_fmac_f32_e32 v48, v57, v57
	v_fmac_f32_e32 v48, v58, v58
	v_fmac_f32_e32 v48, v59, v59
	v_add_f32_e32 v48, v61, v48
	ds_bpermute_b32 v49, v121, v48
	global_store_dwordx4 v[74:75], v[52:55], off offset:512
	global_store_dwordx4 v[74:75], v[56:59], off offset:528
	v_cvt_pk_bf16_f32 v50, v52, v53
	v_cvt_pk_bf16_f32 v51, v54, v55
	v_cvt_pk_bf16_f32 v52, v56, v57
	s_waitcnt lgkmcnt(0)
	v_add_f32_e32 v48, v48, v49
	ds_bpermute_b32 v49, v120, v48
	v_cvt_pk_bf16_f32 v53, v58, v59
	v_lshl_add_u64 v[54:55], v[136:137], 1, s[42:43]
	global_store_dwordx4 v[54:55], v[50:53], off
	s_and_saveexec_b64 s[72:73], s[8:9]
	s_cbranch_execz .LBB0_446
	v_ashrrev_i32_e32 v65, 31, v64
	v_lshl_add_u64 v[50:51], v[64:65], 2, s[68:69]
	s_waitcnt lgkmcnt(0)
	v_add_f32_e32 v48, v48, v49
	global_atomic_add_f32 v[50:51], v48, off
; DI u32x4 pack8(const f32x4& a, const f32x4& b) { u32x4 w; w[0] = pk2(a[0], a[1]); w[1] = pk2(a[2], a[3]); w[2] = pk2(b[0], b[1]); w[3] = pk2(b[2], b[3]); return w; }
;   DI void operator()(const f32x4 (&acc)[2][2][4][2], const Unit& u, int wr, int wc, int fr, int fq) const {
;     ...
;     for (int ai = 0; ai < 2; ++ai)
; #pragma unroll
;       for (int m = 0; m < 4; ++m) {
;         const int r = row0 + ai * HALF + m * 16;
;         float ss = 0.f;
; #pragma unroll
;         for (int bj = 0; bj < 2; ++bj) {
;           const u32 o = (u32)r * 2048u + (u32)(col0 + bj * HALF);
;           const f32x4 x0 = __builtin_nontemporal_load((const f32x4*)(x + o)), x1 = __builtin_nontemporal_load((const f32x4*)(x + o + 4));
;           const f32x4 v0 = x0 + acc[ai][bj][m][0], v1 = x1 + acc[ai][bj][m][1];
;           *(f32x4*)(out + o) = v0; *(f32x4*)(out + o + 4) = v1;
;           *(u32x4*)(x1b + o) = pack8(v0, v1);
;           ss += sq8(v0, v1);
;         }
;         ss += __shfl_xor(ss, 16); ss += __shfl_xor(ss, 32);
;         if (fq == 0) atomicAdd(ssq + r, ss);
;       }
.LBB0_446:
	s_or_b64 exec, exec, s[72:73]
	v_add_u32_e32 v48, 0x90, v146
	v_lshl_add_u32 v136, v48, 11, v168
	v_lshlrev_b64 v[58:59], 2, v[136:137]
	v_lshl_add_u64 v[60:61], s[36:37], 0, v[58:59]
	global_load_dwordx4 v[50:53], v[60:61], off nt
	global_load_dwordx4 v[54:57], v[60:61], off offset:16 nt
	global_load_dwordx4 v[236:239], v[60:61], off offset:512 nt
	global_load_dwordx4 v[240:243], v[60:61], off offset:528 nt
	v_lshl_add_u64 v[62:63], v[136:137], 1, s[42:43]
	v_lshl_add_u64 v[58:59], s[50:51], 0, v[58:59]
	v_or_b32_e32 v136, 0x80, v136
	s_waitcnt vmcnt(3)
	v_pk_add_f32 v[46:47], v[46:47], v[52:53]
	v_pk_add_f32 v[44:45], v[44:45], v[50:51]
	s_waitcnt vmcnt(2)
	v_pk_add_f32 v[42:43], v[42:43], v[56:57]
	v_pk_add_f32 v[40:41], v[40:41], v[54:55]
	v_cvt_pk_bf16_f32 v50, v44, v45
	v_cvt_pk_bf16_f32 v51, v46, v47
	v_cvt_pk_bf16_f32 v52, v40, v41
	v_cvt_pk_bf16_f32 v53, v42, v43
	global_store_dwordx4 v[58:59], v[44:47], off
	global_store_dwordx4 v[58:59], v[40:43], off offset:16
	global_store_dwordx4 v[62:63], v[50:53], off
	s_waitcnt vmcnt(3)
	v_mov_b32_e32 v54, v240
	v_mov_b32_e32 v55, v241
	v_mov_b32_e32 v56, v242
	v_mov_b32_e32 v57, v243
	v_mov_b32_e32 v50, v236
	v_mov_b32_e32 v51, v237
	v_mov_b32_e32 v52, v238
	v_mov_b32_e32 v53, v239
	s_nop 0
	s_nop 0
	v_mul_f32_e32 v45, v45, v45
	v_fmac_f32_e32 v45, v44, v44
	v_fmac_f32_e32 v45, v46, v46
	v_fmac_f32_e32 v45, v47, v47
	v_fmac_f32_e32 v45, v40, v40
	v_fmac_f32_e32 v45, v41, v41
	v_fmac_f32_e32 v45, v42, v42
	v_fmac_f32_e32 v45, v43, v43
	s_nop 0
	v_pk_add_f32 v[36:37], v[36:37], v[50:51]
	s_nop 0
	v_pk_add_f32 v[40:41], v[32:33], v[54:55]
	v_mul_f32_e32 v32, v37, v37
	v_pk_add_f32 v[38:39], v[38:39], v[52:53]
	v_fmac_f32_e32 v32, v36, v36
	v_fmac_f32_e32 v32, v38, v38
	v_fmac_f32_e32 v32, v39, v39
	v_fmac_f32_e32 v32, v40, v40
	v_pk_add_f32 v[42:43], v[34:35], v[56:57]
	v_fmac_f32_e32 v32, v41, v41
	v_fmac_f32_e32 v32, v42, v42
	v_fmac_f32_e32 v32, v43, v43
	v_add_f32_e32 v32, v45, v32
	ds_bpermute_b32 v33, v121, v32
	global_store_dwordx4 v[58:59], v[36:39], off offset:512
	global_store_dwordx4 v[58:59], v[40:43], off offset:528
	v_cvt_pk_bf16_f32 v34, v36, v37
	v_cvt_pk_bf16_f32 v35, v38, v39
	v_cvt_pk_bf16_f32 v36, v40, v41
	s_waitcnt lgkmcnt(0)
	v_add_f32_e32 v32, v32, v33
	ds_bpermute_b32 v33, v120, v32
	v_cvt_pk_bf16_f32 v37, v42, v43
	v_lshl_add_u64 v[38:39], v[136:137], 1, s[42:43]
	global_store_dwordx4 v[38:39], v[34:37], off
	s_and_saveexec_b64 s[72:73], s[8:9]
	s_cbranch_execz .LBB0_448
	v_ashrrev_i32_e32 v49, 31, v48
	v_lshl_add_u64 v[34:35], v[48:49], 2, s[68:69]
	s_waitcnt lgkmcnt(0)
	v_add_f32_e32 v32, v32, v33
	global_atomic_add_f32 v[34:35], v32, off
; DI u32x4 pack8(const f32x4& a, const f32x4& b) { u32x4 w; w[0] = pk2(a[0], a[1]); w[1] = pk2(a[2], a[3]); w[2] = pk2(b[0], b[1]); w[3] = pk2(b[2], b[3]); return w; }
;   DI void operator()(const f32x4 (&acc)[2][2][4][2], const Unit& u, int wr, int wc, int fr, int fq) const {
;     ...
;     for (int ai = 0; ai < 2; ++ai)
; #pragma unroll
;       for (int m = 0; m < 4; ++m) {
;         const int r = row0 + ai * HALF + m * 16;
;         float ss = 0.f;
; #pragma unroll
;         for (int bj = 0; bj < 2; ++bj) {
;           const u32 o = (u32)r * 2048u + (u32)(col0 + bj * HALF);
;           const f32x4 x0 = __builtin_nontemporal_load((const f32x4*)(x + o)), x1 = __builtin_nontemporal_load((const f32x4*)(x + o + 4));
;           const f32x4 v0 = x0 + acc[ai][bj][m][0], v1 = x1 + acc[ai][bj][m][1];
;           *(f32x4*)(out + o) = v0; *(f32x4*)(out + o + 4) = v1;
;           *(u32x4*)(x1b + o) = pack8(v0, v1);
;           ss += sq8(v0, v1);
;         }
;         ss += __shfl_xor(ss, 16); ss += __shfl_xor(ss, 32);
;         if (fq == 0) atomicAdd(ssq + r, ss);
;       }
.LBB0_448:
	s_or_b64 exec, exec, s[72:73]
	v_add_u32_e32 v32, 0xa0, v146
	v_lshl_add_u32 v136, v32, 11, v168
	v_lshlrev_b64 v[42:43], 2, v[136:137]
	v_lshl_add_u64 v[44:45], s[36:37], 0, v[42:43]
	global_load_dwordx4 v[34:37], v[44:45], off nt
	global_load_dwordx4 v[38:41], v[44:45], off offset:16 nt
	global_load_dwordx4 v[236:239], v[44:45], off offset:512 nt
	global_load_dwordx4 v[240:243], v[44:45], off offset:528 nt
	v_lshl_add_u64 v[46:47], v[136:137], 1, s[42:43]
	v_lshl_add_u64 v[42:43], s[50:51], 0, v[42:43]
	v_or_b32_e32 v136, 0x80, v136
	s_waitcnt vmcnt(3)
	v_pk_add_f32 v[30:31], v[30:31], v[36:37]
	v_pk_add_f32 v[28:29], v[28:29], v[34:35]
	s_waitcnt vmcnt(2)
	v_pk_add_f32 v[26:27], v[26:27], v[40:41]
	v_pk_add_f32 v[24:25], v[24:25], v[38:39]
	v_cvt_pk_bf16_f32 v34, v28, v29
	v_cvt_pk_bf16_f32 v35, v30, v31
	v_cvt_pk_bf16_f32 v36, v24, v25
	v_cvt_pk_bf16_f32 v37, v26, v27
	global_store_dwordx4 v[42:43], v[28:31], off
	global_store_dwordx4 v[42:43], v[24:27], off offset:16
	global_store_dwordx4 v[46:47], v[34:37], off
	s_waitcnt vmcnt(3)
	v_mov_b32_e32 v38, v240
	v_mov_b32_e32 v39, v241
	v_mov_b32_e32 v40, v242
	v_mov_b32_e32 v41, v243
	v_mov_b32_e32 v34, v236
	v_mov_b32_e32 v35, v237
	v_mov_b32_e32 v36, v238
	v_mov_b32_e32 v37, v239
	s_nop 0
	s_nop 0
	v_mul_f32_e32 v29, v29, v29
	v_fmac_f32_e32 v29, v28, v28
	v_fmac_f32_e32 v29, v30, v30
	v_fmac_f32_e32 v29, v31, v31
	v_fmac_f32_e32 v29, v24, v24
	v_fmac_f32_e32 v29, v25, v25
	v_fmac_f32_e32 v29, v26, v26
	v_fmac_f32_e32 v29, v27, v27
	s_nop 0
	v_pk_add_f32 v[20:21], v[20:21], v[34:35]
	s_nop 0
	v_pk_add_f32 v[24:25], v[16:17], v[38:39]
	v_mul_f32_e32 v16, v21, v21
	v_pk_add_f32 v[22:23], v[22:23], v[36:37]
	v_fmac_f32_e32 v16, v20, v20
	v_fmac_f32_e32 v16, v22, v22
	v_fmac_f32_e32 v16, v23, v23
	v_fmac_f32_e32 v16, v24, v24
	v_pk_add_f32 v[26:27], v[18:19], v[40:41]
	v_fmac_f32_e32 v16, v25, v25
	v_fmac_f32_e32 v16, v26, v26
	v_fmac_f32_e32 v16, v27, v27
	v_add_f32_e32 v16, v29, v16
	ds_bpermute_b32 v17, v121, v16
	global_store_dwordx4 v[42:43], v[20:23], off offset:512
	global_store_dwordx4 v[42:43], v[24:27], off offset:528
	v_cvt_pk_bf16_f32 v18, v20, v21
	v_cvt_pk_bf16_f32 v19, v22, v23
	v_cvt_pk_bf16_f32 v20, v24, v25
	s_waitcnt lgkmcnt(0)
	v_add_f32_e32 v16, v16, v17
	ds_bpermute_b32 v17, v120, v16
	v_cvt_pk_bf16_f32 v21, v26, v27
	v_lshl_add_u64 v[22:23], v[136:137], 1, s[42:43]
	global_store_dwordx4 v[22:23], v[18:21], off
	s_and_saveexec_b64 s[72:73], s[8:9]
	s_cbranch_execz .LBB0_450
	v_ashrrev_i32_e32 v33, 31, v32
	v_lshl_add_u64 v[18:19], v[32:33], 2, s[68:69]
	s_waitcnt lgkmcnt(0)
	v_add_f32_e32 v16, v16, v17
	global_atomic_add_f32 v[18:19], v16, off
.LBB0_450:
	s_or_b64 exec, exec, s[72:73]
	v_add_u32_e32 v16, 0xb0, v146
	v_lshl_add_u32 v136, v16, 11, v168
	v_lshlrev_b64 v[26:27], 2, v[136:137]
	v_lshl_add_u64 v[28:29], s[36:37], 0, v[26:27]
	global_load_dwordx4 v[18:21], v[28:29], off nt
	global_load_dwordx4 v[22:25], v[28:29], off offset:16 nt
	global_load_dwordx4 v[236:239], v[28:29], off offset:512 nt
	global_load_dwordx4 v[240:243], v[28:29], off offset:528 nt
	v_lshl_add_u64 v[30:31], v[136:137], 1, s[42:43]
	v_lshl_add_u64 v[26:27], s[50:51], 0, v[26:27]
	v_or_b32_e32 v136, 0x80, v136
	s_waitcnt vmcnt(3)
	v_pk_add_f32 v[14:15], v[14:15], v[20:21]
	v_pk_add_f32 v[12:13], v[12:13], v[18:19]
	s_waitcnt vmcnt(2)
	v_pk_add_f32 v[10:11], v[10:11], v[24:25]
	v_pk_add_f32 v[8:9], v[8:9], v[22:23]
	v_cvt_pk_bf16_f32 v18, v12, v13
	v_cvt_pk_bf16_f32 v19, v14, v15
	v_cvt_pk_bf16_f32 v20, v8, v9
	v_cvt_pk_bf16_f32 v21, v10, v11
	global_store_dwordx4 v[26:27], v[12:15], off
	global_store_dwordx4 v[26:27], v[8:11], off offset:16
	global_store_dwordx4 v[30:31], v[18:21], off
	s_waitcnt vmcnt(3)
	v_mov_b32_e32 v22, v240
	v_mov_b32_e32 v23, v241
	v_mov_b32_e32 v24, v242
	v_mov_b32_e32 v25, v243
	v_mov_b32_e32 v18, v236
	v_mov_b32_e32 v19, v237
	v_mov_b32_e32 v20, v238
	v_mov_b32_e32 v21, v239
	s_nop 0
	s_nop 0
	v_mul_f32_e32 v13, v13, v13
	v_fmac_f32_e32 v13, v12, v12
	v_fmac_f32_e32 v13, v14, v14
	v_fmac_f32_e32 v13, v15, v15
	v_fmac_f32_e32 v13, v8, v8
	v_fmac_f32_e32 v13, v9, v9
	v_fmac_f32_e32 v13, v10, v10
	v_fmac_f32_e32 v13, v11, v11
	s_nop 0
	v_pk_add_f32 v[4:5], v[4:5], v[18:19]
	s_nop 0
	v_pk_add_f32 v[8:9], v[0:1], v[22:23]
	v_mul_f32_e32 v0, v5, v5
	v_pk_add_f32 v[6:7], v[6:7], v[20:21]
	v_fmac_f32_e32 v0, v4, v4
	v_fmac_f32_e32 v0, v6, v6
	v_fmac_f32_e32 v0, v7, v7
	v_fmac_f32_e32 v0, v8, v8
	v_pk_add_f32 v[10:11], v[2:3], v[24:25]
	v_fmac_f32_e32 v0, v9, v9
	v_fmac_f32_e32 v0, v10, v10
	v_fmac_f32_e32 v0, v11, v11
	v_add_f32_e32 v0, v13, v0
	ds_bpermute_b32 v1, v121, v0
	global_store_dwordx4 v[26:27], v[4:7], off offset:512
	global_store_dwordx4 v[26:27], v[8:11], off offset:528
	v_cvt_pk_bf16_f32 v2, v4, v5
	v_cvt_pk_bf16_f32 v3, v6, v7
	v_cvt_pk_bf16_f32 v4, v8, v9
	s_waitcnt lgkmcnt(0)
	v_add_f32_e32 v0, v0, v1
	ds_bpermute_b32 v1, v120, v0
	v_cvt_pk_bf16_f32 v5, v10, v11
	v_lshl_add_u64 v[6:7], v[136:137], 1, s[42:43]
	global_store_dwordx4 v[6:7], v[2:5], off
	s_and_saveexec_b64 s[72:73], s[8:9]
	s_cbranch_execz .LBB0_427
	v_ashrrev_i32_e32 v17, 31, v16
	v_lshl_add_u64 v[2:3], v[16:17], 2, s[68:69]
	s_waitcnt lgkmcnt(0)
	v_add_f32_e32 v0, v0, v1
	global_atomic_add_f32 v[2:3], v0, off
	s_branch .LBB0_427
